# speedup vs baseline: 1.0465x; 1.0004x over previous
.LBB0_589:
	s_or_b64 exec, exec, s[4:5]
	s_waitcnt lgkmcnt(0)
	s_barrier
	ds_read_b128 v[2:5], v172
	s_add_i32 s12, s12, s29
	s_cmpk_gt_i32 s12, 0x3ff
	s_waitcnt lgkmcnt(0)
	flat_store_dwordx4 v[138:139], v[2:5] nt
	ds_read_b128 v[2:5], v173
	s_waitcnt lgkmcnt(0)
	flat_store_dwordx4 v[140:141], v[2:5] nt
	ds_read_b128 v[2:5], v174
	s_waitcnt lgkmcnt(0)
	flat_store_dwordx4 v[142:143], v[2:5] nt
	ds_read_b128 v[2:5], v175
	s_waitcnt lgkmcnt(0)
	flat_store_dwordx4 v[144:145], v[2:5] nt
	ds_read_b128 v[2:5], v176
	s_waitcnt lgkmcnt(0)
	flat_store_dwordx4 v[146:147], v[2:5] nt
	ds_read_b128 v[2:5], v177
	s_waitcnt lgkmcnt(0)
	flat_store_dwordx4 v[148:149], v[2:5] nt
	ds_read_b128 v[2:5], v178
	s_waitcnt lgkmcnt(0)
	flat_store_dwordx4 v[150:151], v[2:5] nt
	ds_read_b128 v[2:5], v179
	s_waitcnt lgkmcnt(0)
	flat_store_dwordx4 v[152:153], v[2:5] nt
	ds_read_b128 v[2:5], v180
	s_waitcnt lgkmcnt(0)
	flat_store_dwordx4 v[154:155], v[2:5] nt
	ds_read_b128 v[2:5], v181
	s_waitcnt lgkmcnt(0)
	flat_store_dwordx4 v[156:157], v[2:5] nt
	ds_read_b128 v[2:5], v182
	s_waitcnt lgkmcnt(0)
	flat_store_dwordx4 v[158:159], v[2:5] nt
	ds_read_b128 v[2:5], v183
	s_waitcnt lgkmcnt(0)
	flat_store_dwordx4 v[160:161], v[2:5] nt
	ds_read_b128 v[2:5], v184
	s_waitcnt lgkmcnt(0)
	flat_store_dwordx4 v[162:163], v[2:5] nt
	ds_read_b128 v[2:5], v185
	s_waitcnt lgkmcnt(0)
	flat_store_dwordx4 v[164:165], v[2:5] nt
	ds_read_b128 v[2:5], v186
	s_waitcnt lgkmcnt(0)
	flat_store_dwordx4 v[166:167], v[2:5] nt
	ds_read_b128 v[2:5], v0
	s_waitcnt lgkmcnt(0)
	flat_store_dwordx4 v[168:169], v[2:5] nt
	s_waitcnt lgkmcnt(0)
	s_barrier
	s_cbranch_scc1 .LBB0_587

.LBB0_657:
	s_or_b64 exec, exec, s[6:7]
	s_waitcnt lgkmcnt(0)
	s_barrier
	ds_read_b128 v[2:5], v172
	s_add_i32 s14, s14, s29
	s_cmpk_gt_i32 s14, 0x3ff
	s_waitcnt lgkmcnt(0)
	flat_store_dwordx4 v[138:139], v[2:5] nt
	ds_read_b128 v[2:5], v173
	s_waitcnt lgkmcnt(0)
	flat_store_dwordx4 v[140:141], v[2:5] nt
	ds_read_b128 v[2:5], v174
	s_waitcnt lgkmcnt(0)
	flat_store_dwordx4 v[142:143], v[2:5] nt
	ds_read_b128 v[2:5], v175
	s_waitcnt lgkmcnt(0)
	flat_store_dwordx4 v[144:145], v[2:5] nt
	ds_read_b128 v[2:5], v176
	s_waitcnt lgkmcnt(0)
	flat_store_dwordx4 v[146:147], v[2:5] nt
	ds_read_b128 v[2:5], v177
	s_waitcnt lgkmcnt(0)
	flat_store_dwordx4 v[148:149], v[2:5] nt
	ds_read_b128 v[2:5], v178
	s_waitcnt lgkmcnt(0)
	flat_store_dwordx4 v[150:151], v[2:5] nt
	ds_read_b128 v[2:5], v179
	s_waitcnt lgkmcnt(0)
	flat_store_dwordx4 v[152:153], v[2:5] nt
	ds_read_b128 v[2:5], v180
	s_waitcnt lgkmcnt(0)
	flat_store_dwordx4 v[154:155], v[2:5] nt
	ds_read_b128 v[2:5], v181
	s_waitcnt lgkmcnt(0)
	flat_store_dwordx4 v[156:157], v[2:5] nt
	ds_read_b128 v[2:5], v182
	s_waitcnt lgkmcnt(0)
	flat_store_dwordx4 v[158:159], v[2:5] nt
	ds_read_b128 v[2:5], v183
	s_waitcnt lgkmcnt(0)
	flat_store_dwordx4 v[160:161], v[2:5] nt
	ds_read_b128 v[2:5], v184
	s_waitcnt lgkmcnt(0)
	flat_store_dwordx4 v[162:163], v[2:5] nt
	ds_read_b128 v[2:5], v185
	s_waitcnt lgkmcnt(0)
	flat_store_dwordx4 v[164:165], v[2:5] nt
	ds_read_b128 v[2:5], v186
	s_waitcnt lgkmcnt(0)
	flat_store_dwordx4 v[166:167], v[2:5] nt
	ds_read_b128 v[2:5], v0
	s_waitcnt lgkmcnt(0)
	flat_store_dwordx4 v[168:169], v[2:5] nt
	s_waitcnt lgkmcnt(0)
	s_barrier
	s_cbranch_scc1 .LBB0_684
